# accumulators for the next tile are cleared inside the SWIGLU epilogue while its LDS writes drain; the tile prologue skips its 148 v_mov when the previous epilogue staged the tile
# baseline (speedup 1.0000x reference)
; DI void lds_barrier() { asm volatile("s_waitcnt lgkmcnt(0)\n\ts_barrier" ::: "memory"); }
; #define G_LOAD(RA, RB, KT) { size_t as_ = astep, bs_ = bstep; asm volatile("" : "+s"(as_), "+s"(bs_)); \
;       _Pragma("unroll") for (int i = 0; i < 4; ++i) { RA[i] = *(const u32x4*)(Ag + i * as_ + (KT) * 64); RB[i] = *(const u32x4*)(Bg + i * bs_ + (KT) * 64); } }
; DI void gemm_run(const GemmCfg c, char* smem, float* const g_h, u16* const g_hb, float* const g_out, const int final_out) {
;     ...
;     f32x16 acc[2][4];
; #pragma unroll
;     for (int a = 0; a < 2; ++a)
; #pragma unroll
;       for (int b = 0; b < 4; ++b)
; #pragma unroll
;         for (int i = 0; i < 16; ++i) acc[a][b][i] = 0.f;
;     float ss[4] = {0.f, 0.f, 0.f, 0.f};
;     u32x4 ra0[4], rb0[4];
;     ...
;     G_LOAD(ra0, rb0, 0);
;     __syncthreads();
;     G_STORE(ra0, rb0, 0);
;     G_LOAD(ra0, rb0, 1);
;     lds_barrier();
.Lgemm_pf_skip:
	s_mov_b32 s1, 0
	s_nop 0
	v_writelane_b32 v255, s1, 51
	s_add_u32 s4, s4, 0x80
	s_addc_u32 s5, s5, 0
	s_add_u32 s6, s6, 0x80
	s_addc_u32 s7, s7, 0
	s_add_u32 m0, s8, 0x9000
	s_nop 0
	global_load_lds_dwordx4 v130, s[4:5]
	s_add_u32 m0, s8, 0x1b000
	s_nop 0
	global_load_lds_dwordx4 v134, s[6:7]
	s_add_u32 m0, s8, 0x9400
	s_nop 0
	global_load_lds_dwordx4 v131, s[4:5]
	s_add_u32 m0, s8, 0x1b400
	s_nop 0
	global_load_lds_dwordx4 v135, s[6:7]
	s_add_u32 m0, s8, 0x9800
	s_nop 0
	global_load_lds_dwordx4 v132, s[4:5]
	s_add_u32 m0, s8, 0x1b800
	s_nop 0
	global_load_lds_dwordx4 v136, s[6:7]
	s_add_u32 m0, s8, 0x9c00
	s_nop 0
	global_load_lds_dwordx4 v133, s[4:5]
	s_add_u32 m0, s8, 0x1bc00
	s_nop 0
	global_load_lds_dwordx4 v137, s[6:7]
	s_add_u32 s4, s4, 0x80
	s_addc_u32 s5, s5, 0
	s_add_u32 s6, s6, 0x80
	s_addc_u32 s7, s7, 0
	s_cmp_lg_u32 s0, 0
	s_cbranch_scc1 .Lgemm_zero_skip
	v_mov_b32_e32 v0, 0
	v_mov_b32_e32 v1, 0
	v_mov_b32_e32 v2, 0
	v_mov_b32_e32 v3, 0
	v_mov_b32_e32 v4, 0
	v_mov_b32_e32 v5, 0
	v_mov_b32_e32 v6, 0
	v_mov_b32_e32 v7, 0
	v_mov_b32_e32 v8, 0
	v_mov_b32_e32 v9, 0
	v_mov_b32_e32 v10, 0
	v_mov_b32_e32 v11, 0
	v_mov_b32_e32 v12, 0
	v_mov_b32_e32 v13, 0
	v_mov_b32_e32 v14, 0
	v_mov_b32_e32 v15, 0
	v_mov_b32_e32 v16, 0
	v_mov_b32_e32 v17, 0
	v_mov_b32_e32 v18, 0
	v_mov_b32_e32 v19, 0
	v_mov_b32_e32 v20, 0
	v_mov_b32_e32 v21, 0
	v_mov_b32_e32 v22, 0
	v_mov_b32_e32 v23, 0
	v_mov_b32_e32 v24, 0
	v_mov_b32_e32 v25, 0
	v_mov_b32_e32 v26, 0
	v_mov_b32_e32 v27, 0
	v_mov_b32_e32 v28, 0
	v_mov_b32_e32 v29, 0
	v_mov_b32_e32 v30, 0
	v_mov_b32_e32 v31, 0
	v_mov_b32_e32 v32, 0
	v_mov_b32_e32 v33, 0
	v_mov_b32_e32 v34, 0
	v_mov_b32_e32 v35, 0
	v_mov_b32_e32 v36, 0
	v_mov_b32_e32 v37, 0
	v_mov_b32_e32 v38, 0
	v_mov_b32_e32 v39, 0
	v_mov_b32_e32 v40, 0
	v_mov_b32_e32 v41, 0
	v_mov_b32_e32 v42, 0
	v_mov_b32_e32 v43, 0
	v_mov_b32_e32 v44, 0
	v_mov_b32_e32 v45, 0
	v_mov_b32_e32 v46, 0
	v_mov_b32_e32 v47, 0
	v_mov_b32_e32 v48, 0
	v_mov_b32_e32 v49, 0
	v_mov_b32_e32 v50, 0
	v_mov_b32_e32 v51, 0
	v_mov_b32_e32 v52, 0
	v_mov_b32_e32 v53, 0
	v_mov_b32_e32 v54, 0
	v_mov_b32_e32 v55, 0
	v_mov_b32_e32 v56, 0
	v_mov_b32_e32 v57, 0
	v_mov_b32_e32 v58, 0
	v_mov_b32_e32 v59, 0
	v_mov_b32_e32 v60, 0
	v_mov_b32_e32 v61, 0
	v_mov_b32_e32 v62, 0
	v_mov_b32_e32 v63, 0
	v_mov_b32_e32 v64, 0
	v_mov_b32_e32 v65, 0
	v_mov_b32_e32 v66, 0
	v_mov_b32_e32 v67, 0
	v_mov_b32_e32 v68, 0
	v_mov_b32_e32 v69, 0
	v_mov_b32_e32 v70, 0
	v_mov_b32_e32 v71, 0
	v_mov_b32_e32 v72, 0
	v_mov_b32_e32 v73, 0
	v_mov_b32_e32 v74, 0
	v_mov_b32_e32 v75, 0
	v_mov_b32_e32 v76, 0
	v_mov_b32_e32 v77, 0
	v_mov_b32_e32 v78, 0
	v_mov_b32_e32 v79, 0
	v_mov_b32_e32 v80, 0
	v_mov_b32_e32 v81, 0
	v_mov_b32_e32 v82, 0
	v_mov_b32_e32 v83, 0
	v_mov_b32_e32 v84, 0
	v_mov_b32_e32 v85, 0
	v_mov_b32_e32 v86, 0
	v_mov_b32_e32 v87, 0
	v_mov_b32_e32 v88, 0
	v_mov_b32_e32 v89, 0
	v_mov_b32_e32 v90, 0
	v_mov_b32_e32 v91, 0
	v_mov_b32_e32 v92, 0
	v_mov_b32_e32 v93, 0
	v_mov_b32_e32 v94, 0
	v_mov_b32_e32 v95, 0
	v_mov_b32_e32 v96, 0
	v_mov_b32_e32 v97, 0
	v_mov_b32_e32 v98, 0
	v_mov_b32_e32 v99, 0
	v_mov_b32_e32 v100, 0
	v_mov_b32_e32 v101, 0
	v_mov_b32_e32 v102, 0
	v_mov_b32_e32 v103, 0
	v_mov_b32_e32 v104, 0
	v_mov_b32_e32 v105, 0
	v_mov_b32_e32 v106, 0
	v_mov_b32_e32 v107, 0
	v_mov_b32_e32 v108, 0
	v_mov_b32_e32 v109, 0
	v_mov_b32_e32 v110, 0
	v_mov_b32_e32 v111, 0
	v_mov_b32_e32 v112, 0
	v_mov_b32_e32 v113, 0
	v_mov_b32_e32 v114, 0
	v_mov_b32_e32 v115, 0
	v_mov_b32_e32 v116, 0
	v_mov_b32_e32 v117, 0
	v_mov_b32_e32 v118, 0
	v_mov_b32_e32 v119, 0
	v_mov_b32_e32 v120, 0
	v_mov_b32_e32 v121, 0
	v_mov_b32_e32 v122, 0
	v_mov_b32_e32 v123, 0
	v_mov_b32_e32 v124, 0
	v_mov_b32_e32 v125, 0
	v_mov_b32_e32 v126, 0
	v_mov_b32_e32 v127, 0
	v_mov_b32_e32 v199, 0
	v_mov_b32_e32 v198, 0
	v_mov_b32_e32 v171, 0
	v_mov_b32_e32 v164, 0
	v_mov_b32_e32 v140, 0
	v_mov_b32_e32 v141, 0
	v_mov_b32_e32 v142, 0
	v_mov_b32_e32 v143, 0
	v_mov_b32_e32 v144, 0
	v_mov_b32_e32 v145, 0
	v_mov_b32_e32 v146, 0
	v_mov_b32_e32 v147, 0
	v_mov_b32_e32 v148, 0
	v_mov_b32_e32 v149, 0
	v_mov_b32_e32 v150, 0
	v_mov_b32_e32 v151, 0
	v_mov_b32_e32 v152, 0
	v_mov_b32_e32 v153, 0
	v_mov_b32_e32 v154, 0
	v_mov_b32_e32 v155, 0
.Lgemm_zero_skip:
	s_waitcnt vmcnt(8)
	s_mov_b32 s1, 0
	s_add_i32 s0, s68, 3
	s_barrier
	ds_read_b128 v[160:163], v194
	ds_read_b128 v[176:179], v194 offset:2048
	ds_read_b128 v[180:183], v194 offset:4096
	ds_read_b128 v[204:207], v195
	ds_read_b128 v[222:225], v195 offset:2048
	ds_read_b128 v[226:229], v195 offset:4096
	ds_read_b128 v[230:233], v195 offset:6144
	ds_read_b128 v[234:237], v195 offset:8192
	ds_read_b128 v[238:241], v195 offset:10240
	ds_read_b128 v[242:245], v195 offset:12288
	ds_read_b128 v[246:249], v195 offset:14336
	ds_read_b128 v[200:203], v194 offset:6144
	s_cmp_ge_u32 s8, 0x4000
	s_cbranch_scc1 .Lgemm_disp_late
	s_cmp_eq_u32 s9, 0
	s_cbranch_scc1 .Lgemm_kloop_n
	s_cmp_eq_u32 s9, 2
	s_cbranch_scc1 .Lgemm_kloop_r1e
	s_branch .LBB0_112

; DI void epi_slab(const GemmCfg c, const f32x16 (&acc)[4], float* sW, const float* rss, const size_t row0, const int g, const int lane,
;                  float* const g_h, u16* const g_hb, float* const g_out, const int final_out) {
;     ...
;   if (c.epi == EPI_SWIGLU) {
;     const int c4 = (ln_ & 15) * 4;
; #pragma unroll 2
;     for (int it = 0; it < 8; ++it) {
;       const int r = (ln_ >> 4) + 4 * it;
;       const float rs = rsqrtf(rss[r] * invK + 1e-6f);
;       f32x4 a = *(const f32x4*)(sW + r * 132 + c4);
;       f32x4 b = *(const f32x4*)(sW + r * 132 + 64 + c4);
;       float y[4];
; #pragma unroll
;       for (int e = 0; e < 4; ++e) { float av = a[e] * rs, bv = b[e] * rs; y[e] = av * __builtin_amdgcn_rcpf(1.f + __expf(-av)) * bv; }
;       *(u32x2*)(c.o16 + (row0 + r) * DFF + g * 64 + c4) = MK2(pack2(y[0], y[1]), pack2(y[2], y[3]));
;     }
.Lswg2_nopf:
	s_nop 0
	v_writelane_b32 v255, s9, 51
	s_mov_b64 s[8:9], 0
	s_waitcnt lgkmcnt(0)
	v_fmaak_f32 v226, v191, v226, 0x358637bd
	v_fmaak_f32 v227, v191, v227, 0x358637bd
	v_rsq_f32_e32 v226, v226
	v_rsq_f32_e32 v227, v227
	v_fmaak_f32 v228, v191, v228, 0x358637bd
	v_fmaak_f32 v229, v191, v229, 0x358637bd
	v_rsq_f32_e32 v228, v228
	v_rsq_f32_e32 v229, v229
	v_fmaak_f32 v230, v191, v230, 0x358637bd
	v_fmaak_f32 v231, v191, v231, 0x358637bd
	v_rsq_f32_e32 v230, v230
	v_rsq_f32_e32 v231, v231
	v_fmaak_f32 v232, v191, v232, 0x358637bd
	v_fmaak_f32 v233, v191, v233, 0x358637bd
	v_rsq_f32_e32 v232, v232
	v_rsq_f32_e32 v233, v233
	v_fmaak_f32 v234, v191, v234, 0x358637bd
	v_fmaak_f32 v235, v191, v235, 0x358637bd
	v_rsq_f32_e32 v234, v234
	v_rsq_f32_e32 v235, v235
	v_fmaak_f32 v236, v191, v236, 0x358637bd
	v_fmaak_f32 v237, v191, v237, 0x358637bd
	v_rsq_f32_e32 v236, v236
	v_rsq_f32_e32 v237, v237
	v_fmaak_f32 v238, v191, v238, 0x358637bd
	v_fmaak_f32 v239, v191, v239, 0x358637bd
	v_rsq_f32_e32 v238, v238
	v_rsq_f32_e32 v239, v239
	v_fmaak_f32 v240, v191, v240, 0x358637bd
	v_fmaak_f32 v241, v191, v241, 0x358637bd
	v_rsq_f32_e32 v240, v240
	v_rsq_f32_e32 v241, v241
	s_nop 0
	v_pk_mul_f32 v[64:65], v[64:65], v[226:227]
	v_pk_mul_f32 v[66:67], v[66:67], v[228:229]
	v_pk_mul_f32 v[80:81], v[80:81], v[226:227]
	v_pk_mul_f32 v[82:83], v[82:83], v[228:229]
	v_mul_f32_e32 v242, 0xbfb8aa3b, v64
	v_mul_f32_e32 v243, 0xbfb8aa3b, v65
	v_mul_f32_e32 v244, 0xbfb8aa3b, v66
	v_mul_f32_e32 v245, 0xbfb8aa3b, v67
	v_exp_f32_e32 v242, v242
	v_exp_f32_e32 v243, v243
	v_exp_f32_e32 v244, v244
	v_exp_f32_e32 v245, v245
	v_add_f32_e32 v242, 1.0, v242
	v_add_f32_e32 v243, 1.0, v243
	v_add_f32_e32 v244, 1.0, v244
	v_add_f32_e32 v245, 1.0, v245
	v_rcp_f32_e32 v242, v242
	v_rcp_f32_e32 v243, v243
	v_rcp_f32_e32 v244, v244
	v_rcp_f32_e32 v245, v245
	s_nop 0
	v_pk_mul_f32 v[64:65], v[64:65], v[242:243]
	v_pk_mul_f32 v[66:67], v[66:67], v[244:245]
	v_pk_mul_f32 v[64:65], v[80:81], v[64:65]
	v_pk_mul_f32 v[66:67], v[82:83], v[66:67]
	ds_write2_b32 v198, v64, v65 offset0:0 offset1:68
	ds_write2_b32 v198, v66, v67 offset0:136 offset1:204
	v_pk_mul_f32 v[68:69], v[68:69], v[226:227]
	v_pk_mul_f32 v[70:71], v[70:71], v[228:229]
	v_pk_mul_f32 v[84:85], v[84:85], v[226:227]
	v_pk_mul_f32 v[86:87], v[86:87], v[228:229]
	v_mul_f32_e32 v242, 0xbfb8aa3b, v68
	v_mul_f32_e32 v243, 0xbfb8aa3b, v69
	v_mul_f32_e32 v244, 0xbfb8aa3b, v70
	v_mul_f32_e32 v245, 0xbfb8aa3b, v71
	v_exp_f32_e32 v242, v242
	v_exp_f32_e32 v243, v243
	v_exp_f32_e32 v244, v244
	v_exp_f32_e32 v245, v245
	v_add_f32_e32 v242, 1.0, v242
	v_add_f32_e32 v243, 1.0, v243
	v_add_f32_e32 v244, 1.0, v244
	v_add_f32_e32 v245, 1.0, v245
	v_rcp_f32_e32 v242, v242
	v_rcp_f32_e32 v243, v243
	v_rcp_f32_e32 v244, v244
	v_rcp_f32_e32 v245, v245
	s_nop 0
	v_pk_mul_f32 v[68:69], v[68:69], v[242:243]
	v_pk_mul_f32 v[70:71], v[70:71], v[244:245]
	v_pk_mul_f32 v[68:69], v[84:85], v[68:69]
	v_pk_mul_f32 v[70:71], v[86:87], v[70:71]
	ds_write2_b32 v198, v68, v69 offset0:16 offset1:84
	ds_write2_b32 v198, v70, v71 offset0:152 offset1:220
	v_pk_mul_f32 v[72:73], v[72:73], v[226:227]
	v_pk_mul_f32 v[74:75], v[74:75], v[228:229]
	v_pk_mul_f32 v[88:89], v[88:89], v[226:227]
	v_pk_mul_f32 v[90:91], v[90:91], v[228:229]
	v_mul_f32_e32 v242, 0xbfb8aa3b, v72
	v_mul_f32_e32 v243, 0xbfb8aa3b, v73
	v_mul_f32_e32 v244, 0xbfb8aa3b, v74
	v_mul_f32_e32 v245, 0xbfb8aa3b, v75
	v_exp_f32_e32 v242, v242
	v_exp_f32_e32 v243, v243
	v_exp_f32_e32 v244, v244
	v_exp_f32_e32 v245, v245
	v_add_f32_e32 v242, 1.0, v242
	v_add_f32_e32 v243, 1.0, v243
	v_add_f32_e32 v244, 1.0, v244
	v_add_f32_e32 v245, 1.0, v245
	v_rcp_f32_e32 v242, v242
	v_rcp_f32_e32 v243, v243
	v_rcp_f32_e32 v244, v244
	v_rcp_f32_e32 v245, v245
	s_nop 0
	v_pk_mul_f32 v[72:73], v[72:73], v[242:243]
	v_pk_mul_f32 v[74:75], v[74:75], v[244:245]
	v_pk_mul_f32 v[72:73], v[88:89], v[72:73]
	v_pk_mul_f32 v[74:75], v[90:91], v[74:75]
	ds_write2_b32 v198, v72, v73 offset0:32 offset1:100
	ds_write2_b32 v198, v74, v75 offset0:168 offset1:236
	v_pk_mul_f32 v[76:77], v[76:77], v[226:227]
	v_pk_mul_f32 v[78:79], v[78:79], v[228:229]
	v_pk_mul_f32 v[92:93], v[92:93], v[226:227]
	v_pk_mul_f32 v[94:95], v[94:95], v[228:229]
	v_mul_f32_e32 v242, 0xbfb8aa3b, v76
	v_mul_f32_e32 v243, 0xbfb8aa3b, v77
	v_mul_f32_e32 v244, 0xbfb8aa3b, v78
	v_mul_f32_e32 v245, 0xbfb8aa3b, v79
	v_exp_f32_e32 v242, v242
	v_exp_f32_e32 v243, v243
	v_exp_f32_e32 v244, v244
	v_exp_f32_e32 v245, v245
	v_add_f32_e32 v242, 1.0, v242
	v_add_f32_e32 v243, 1.0, v243
	v_add_f32_e32 v244, 1.0, v244
	v_add_f32_e32 v245, 1.0, v245
	v_rcp_f32_e32 v242, v242
	v_rcp_f32_e32 v243, v243
	v_rcp_f32_e32 v244, v244
	v_rcp_f32_e32 v245, v245
	s_nop 0
	v_pk_mul_f32 v[76:77], v[76:77], v[242:243]
	v_pk_mul_f32 v[78:79], v[78:79], v[244:245]
	v_pk_mul_f32 v[76:77], v[92:93], v[76:77]
	v_pk_mul_f32 v[78:79], v[94:95], v[78:79]
	ds_write2_b32 v198, v76, v77 offset0:48 offset1:116
	ds_write2_b32 v198, v78, v79 offset0:184 offset1:252
	v_pk_mul_f32 v[96:97], v[96:97], v[230:231]
	v_pk_mul_f32 v[98:99], v[98:99], v[232:233]
	v_pk_mul_f32 v[112:113], v[112:113], v[230:231]
	v_pk_mul_f32 v[114:115], v[114:115], v[232:233]
	v_mul_f32_e32 v242, 0xbfb8aa3b, v96
	v_mul_f32_e32 v243, 0xbfb8aa3b, v97
	v_mul_f32_e32 v244, 0xbfb8aa3b, v98
	v_mul_f32_e32 v245, 0xbfb8aa3b, v99
	v_exp_f32_e32 v242, v242
	v_exp_f32_e32 v243, v243
	v_exp_f32_e32 v244, v244
	v_exp_f32_e32 v245, v245
	v_add_f32_e32 v242, 1.0, v242
	v_add_f32_e32 v243, 1.0, v243
	v_add_f32_e32 v244, 1.0, v244
	v_add_f32_e32 v245, 1.0, v245
	v_rcp_f32_e32 v242, v242
	v_rcp_f32_e32 v243, v243
	v_rcp_f32_e32 v244, v244
; DI void epi_slab(const GemmCfg c, const f32x16 (&acc)[4], float* sW, const float* rss, const size_t row0, const int g, const int lane,
;                  float* const g_h, u16* const g_hb, float* const g_out, const int final_out) {
;     ...
;   if (c.epi == EPI_SWIGLU) {
;     const int c4 = (ln_ & 15) * 4;
; #pragma unroll 2
;     for (int it = 0; it < 8; ++it) {
;       const int r = (ln_ >> 4) + 4 * it;
;       const float rs = rsqrtf(rss[r] * invK + 1e-6f);
;       f32x4 a = *(const f32x4*)(sW + r * 132 + c4);
;       f32x4 b = *(const f32x4*)(sW + r * 132 + 64 + c4);
;       float y[4];
; #pragma unroll
;       for (int e = 0; e < 4; ++e) { float av = a[e] * rs, bv = b[e] * rs; y[e] = av * __builtin_amdgcn_rcpf(1.f + __expf(-av)) * bv; }
;       *(u32x2*)(c.o16 + (row0 + r) * DFF + g * 64 + c4) = MK2(pack2(y[0], y[1]), pack2(y[2], y[3]));
;     }
; DI void gemm_run(const GemmCfg c, char* smem, float* const g_h, u16* const g_hb, float* const g_out, const int final_out) {
;     ...
;     f32x16 acc[2][4];
; #pragma unroll
;     for (int a = 0; a < 2; ++a)
; #pragma unroll
;       for (int b = 0; b < 4; ++b)
; #pragma unroll
;         for (int i = 0; i < 16; ++i) acc[a][b][i] = 0.f;
	v_rcp_f32_e32 v245, v245
	s_nop 0
	v_pk_mul_f32 v[96:97], v[96:97], v[242:243]
	v_pk_mul_f32 v[98:99], v[98:99], v[244:245]
	v_pk_mul_f32 v[96:97], v[112:113], v[96:97]
	v_pk_mul_f32 v[98:99], v[114:115], v[98:99]
	ds_write2_b32 v199, v96, v97 offset0:0 offset1:68
	ds_write2_b32 v199, v98, v99 offset0:136 offset1:204
	v_pk_mul_f32 v[100:101], v[100:101], v[230:231]
	v_pk_mul_f32 v[102:103], v[102:103], v[232:233]
	v_pk_mul_f32 v[116:117], v[116:117], v[230:231]
	v_pk_mul_f32 v[118:119], v[118:119], v[232:233]
	v_mul_f32_e32 v242, 0xbfb8aa3b, v100
	v_mul_f32_e32 v243, 0xbfb8aa3b, v101
	v_mul_f32_e32 v244, 0xbfb8aa3b, v102
	v_mul_f32_e32 v245, 0xbfb8aa3b, v103
	v_exp_f32_e32 v242, v242
	v_exp_f32_e32 v243, v243
	v_exp_f32_e32 v244, v244
	v_exp_f32_e32 v245, v245
	v_add_f32_e32 v242, 1.0, v242
	v_add_f32_e32 v243, 1.0, v243
	v_add_f32_e32 v244, 1.0, v244
	v_add_f32_e32 v245, 1.0, v245
	v_rcp_f32_e32 v242, v242
	v_rcp_f32_e32 v243, v243
	v_rcp_f32_e32 v244, v244
	v_rcp_f32_e32 v245, v245
	s_nop 0
	v_pk_mul_f32 v[100:101], v[100:101], v[242:243]
	v_pk_mul_f32 v[102:103], v[102:103], v[244:245]
	v_pk_mul_f32 v[100:101], v[116:117], v[100:101]
	v_pk_mul_f32 v[102:103], v[118:119], v[102:103]
	ds_write2_b32 v199, v100, v101 offset0:16 offset1:84
	ds_write2_b32 v199, v102, v103 offset0:152 offset1:220
	v_pk_mul_f32 v[104:105], v[104:105], v[230:231]
	v_pk_mul_f32 v[106:107], v[106:107], v[232:233]
	v_pk_mul_f32 v[120:121], v[120:121], v[230:231]
	v_pk_mul_f32 v[122:123], v[122:123], v[232:233]
	v_mul_f32_e32 v242, 0xbfb8aa3b, v104
	v_mul_f32_e32 v243, 0xbfb8aa3b, v105
	v_mul_f32_e32 v244, 0xbfb8aa3b, v106
	v_mul_f32_e32 v245, 0xbfb8aa3b, v107
	v_exp_f32_e32 v242, v242
	v_exp_f32_e32 v243, v243
	v_exp_f32_e32 v244, v244
	v_exp_f32_e32 v245, v245
	v_add_f32_e32 v242, 1.0, v242
	v_add_f32_e32 v243, 1.0, v243
	v_add_f32_e32 v244, 1.0, v244
	v_add_f32_e32 v245, 1.0, v245
	v_rcp_f32_e32 v242, v242
	v_rcp_f32_e32 v243, v243
	v_rcp_f32_e32 v244, v244
	v_rcp_f32_e32 v245, v245
	s_nop 0
	v_pk_mul_f32 v[104:105], v[104:105], v[242:243]
	v_pk_mul_f32 v[106:107], v[106:107], v[244:245]
	v_pk_mul_f32 v[104:105], v[120:121], v[104:105]
	v_pk_mul_f32 v[106:107], v[122:123], v[106:107]
	ds_write2_b32 v199, v104, v105 offset0:32 offset1:100
	ds_write2_b32 v199, v106, v107 offset0:168 offset1:236
	v_pk_mul_f32 v[108:109], v[108:109], v[230:231]
	v_pk_mul_f32 v[110:111], v[110:111], v[232:233]
	v_pk_mul_f32 v[124:125], v[124:125], v[230:231]
	v_pk_mul_f32 v[126:127], v[126:127], v[232:233]
	v_mul_f32_e32 v242, 0xbfb8aa3b, v108
	v_mul_f32_e32 v243, 0xbfb8aa3b, v109
	v_mul_f32_e32 v244, 0xbfb8aa3b, v110
	v_mul_f32_e32 v245, 0xbfb8aa3b, v111
	v_exp_f32_e32 v242, v242
	v_exp_f32_e32 v243, v243
	v_exp_f32_e32 v244, v244
	v_exp_f32_e32 v245, v245
	v_add_f32_e32 v242, 1.0, v242
	v_add_f32_e32 v243, 1.0, v243
	v_add_f32_e32 v244, 1.0, v244
	v_add_f32_e32 v245, 1.0, v245
	v_rcp_f32_e32 v242, v242
	v_rcp_f32_e32 v243, v243
	v_rcp_f32_e32 v244, v244
	v_rcp_f32_e32 v245, v245
	s_nop 0
	v_pk_mul_f32 v[108:109], v[108:109], v[242:243]
	v_pk_mul_f32 v[110:111], v[110:111], v[244:245]
	v_pk_mul_f32 v[108:109], v[124:125], v[108:109]
	v_pk_mul_f32 v[110:111], v[126:127], v[110:111]
	ds_write2_b32 v199, v108, v109 offset0:48 offset1:116
	ds_write2_b32 v199, v110, v111 offset0:184 offset1:252
	v_mov_b32_e32 v64, 0
	v_mov_b32_e32 v65, 0
	v_mov_b32_e32 v66, 0
	v_mov_b32_e32 v67, 0
	v_mov_b32_e32 v68, 0
	v_mov_b32_e32 v69, 0
	v_mov_b32_e32 v70, 0
	v_mov_b32_e32 v71, 0
	v_mov_b32_e32 v72, 0
	v_mov_b32_e32 v73, 0
	v_mov_b32_e32 v74, 0
	v_mov_b32_e32 v75, 0
	v_mov_b32_e32 v76, 0
	v_mov_b32_e32 v77, 0
	v_mov_b32_e32 v78, 0
	v_mov_b32_e32 v79, 0
	v_mov_b32_e32 v96, 0
	v_mov_b32_e32 v97, 0
	v_mov_b32_e32 v98, 0
	v_mov_b32_e32 v99, 0
	v_mov_b32_e32 v100, 0
	v_mov_b32_e32 v101, 0
	v_mov_b32_e32 v102, 0
	v_mov_b32_e32 v103, 0
	v_mov_b32_e32 v104, 0
	v_mov_b32_e32 v105, 0
	v_mov_b32_e32 v106, 0
	v_mov_b32_e32 v107, 0
	v_mov_b32_e32 v108, 0
	v_mov_b32_e32 v109, 0
	v_mov_b32_e32 v110, 0
	v_mov_b32_e32 v111, 0
	s_waitcnt lgkmcnt(0)
	ds_read_b128 v[80:83], v200
	ds_read_b128 v[84:87], v200 offset:1088
	ds_read_b128 v[88:91], v200 offset:2176
	ds_read_b128 v[92:95], v200 offset:3264
	ds_read_b128 v[112:115], v200 offset:4352
	ds_read_b128 v[116:119], v200 offset:5440
	ds_read_b128 v[120:123], v200 offset:6528
	ds_read_b128 v[124:127], v200 offset:7616
	s_waitcnt lgkmcnt(7)
	v_lshl_add_u64 v[204:205], v[202:203], 0, s[8:9]
	v_cvt_pk_bf16_f32 v80, v80, v81
	v_cvt_pk_bf16_f32 v81, v82, v83
	s_add_u32 s8, s8, 0x5800
	s_addc_u32 s9, s9, 0
	global_store_dwordx2 v[204:205], v[80:81], off
	s_waitcnt lgkmcnt(6)
	v_lshl_add_u64 v[204:205], v[202:203], 0, s[8:9]
	v_cvt_pk_bf16_f32 v84, v84, v85
	v_cvt_pk_bf16_f32 v85, v86, v87
	s_add_u32 s8, s8, 0x5800
	s_addc_u32 s9, s9, 0
	global_store_dwordx2 v[204:205], v[84:85], off
	s_waitcnt lgkmcnt(5)
	v_lshl_add_u64 v[204:205], v[202:203], 0, s[8:9]
	v_cvt_pk_bf16_f32 v88, v88, v89
	v_cvt_pk_bf16_f32 v89, v90, v91
	s_add_u32 s8, s8, 0x5800
	s_addc_u32 s9, s9, 0
	global_store_dwordx2 v[204:205], v[88:89], off
	s_waitcnt lgkmcnt(4)
	v_lshl_add_u64 v[204:205], v[202:203], 0, s[8:9]
	v_cvt_pk_bf16_f32 v92, v92, v93
	v_cvt_pk_bf16_f32 v93, v94, v95
	s_add_u32 s8, s8, 0x5800
	s_addc_u32 s9, s9, 0
	global_store_dwordx2 v[204:205], v[92:93], off
	s_waitcnt lgkmcnt(3)
	v_lshl_add_u64 v[204:205], v[202:203], 0, s[8:9]
	v_cvt_pk_bf16_f32 v112, v112, v113
	v_cvt_pk_bf16_f32 v113, v114, v115
	s_add_u32 s8, s8, 0x5800
	s_addc_u32 s9, s9, 0
	global_store_dwordx2 v[204:205], v[112:113], off
	s_waitcnt lgkmcnt(2)
; DI void epi_slab(const GemmCfg c, const f32x16 (&acc)[4], float* sW, const float* rss, const size_t row0, const int g, const int lane,
;                  float* const g_h, u16* const g_hb, float* const g_out, const int final_out) {
;     ...
;   if (c.epi == EPI_SWIGLU) {
;     const int c4 = (ln_ & 15) * 4;
; #pragma unroll 2
;     for (int it = 0; it < 8; ++it) {
;       const int r = (ln_ >> 4) + 4 * it;
;       const float rs = rsqrtf(rss[r] * invK + 1e-6f);
;       f32x4 a = *(const f32x4*)(sW + r * 132 + c4);
;       f32x4 b = *(const f32x4*)(sW + r * 132 + 64 + c4);
;       float y[4];
; #pragma unroll
;       for (int e = 0; e < 4; ++e) { float av = a[e] * rs, bv = b[e] * rs; y[e] = av * __builtin_amdgcn_rcpf(1.f + __expf(-av)) * bv; }
;       *(u32x2*)(c.o16 + (row0 + r) * DFF + g * 64 + c4) = MK2(pack2(y[0], y[1]), pack2(y[2], y[3]));
;     }
	v_lshl_add_u64 v[204:205], v[202:203], 0, s[8:9]
	v_cvt_pk_bf16_f32 v116, v116, v117
	v_cvt_pk_bf16_f32 v117, v118, v119
	s_add_u32 s8, s8, 0x5800
	s_addc_u32 s9, s9, 0
	global_store_dwordx2 v[204:205], v[116:117], off
	s_waitcnt lgkmcnt(1)
	v_lshl_add_u64 v[204:205], v[202:203], 0, s[8:9]
	v_cvt_pk_bf16_f32 v120, v120, v121
	v_cvt_pk_bf16_f32 v121, v122, v123
	s_add_u32 s8, s8, 0x5800
	s_addc_u32 s9, s9, 0
	global_store_dwordx2 v[204:205], v[120:121], off
	s_waitcnt lgkmcnt(0)
	v_lshl_add_u64 v[204:205], v[202:203], 0, s[8:9]
	v_cvt_pk_bf16_f32 v124, v124, v125
	v_cvt_pk_bf16_f32 v125, v126, v127
	s_add_u32 s8, s8, 0x5800
	s_addc_u32 s9, s9, 0
	global_store_dwordx2 v[204:205], v[124:125], off
	v_pk_mul_f32 v[0:1], v[0:1], v[234:235]
	v_pk_mul_f32 v[2:3], v[2:3], v[236:237]
	v_pk_mul_f32 v[16:17], v[16:17], v[234:235]
	v_pk_mul_f32 v[18:19], v[18:19], v[236:237]
	v_mul_f32_e32 v242, 0xbfb8aa3b, v0
	v_mul_f32_e32 v243, 0xbfb8aa3b, v1
	v_mul_f32_e32 v244, 0xbfb8aa3b, v2
	v_mul_f32_e32 v245, 0xbfb8aa3b, v3
	v_exp_f32_e32 v242, v242
	v_exp_f32_e32 v243, v243
	v_exp_f32_e32 v244, v244
	v_exp_f32_e32 v245, v245
	v_add_f32_e32 v242, 1.0, v242
	v_add_f32_e32 v243, 1.0, v243
	v_add_f32_e32 v244, 1.0, v244
	v_add_f32_e32 v245, 1.0, v245
	v_rcp_f32_e32 v242, v242
	v_rcp_f32_e32 v243, v243
	v_rcp_f32_e32 v244, v244
	v_rcp_f32_e32 v245, v245
	s_nop 0
	v_pk_mul_f32 v[0:1], v[0:1], v[242:243]
	v_pk_mul_f32 v[2:3], v[2:3], v[244:245]
	v_pk_mul_f32 v[0:1], v[16:17], v[0:1]
	v_pk_mul_f32 v[2:3], v[18:19], v[2:3]
	ds_write2_b32 v198, v0, v1 offset0:0 offset1:68
	ds_write2_b32 v198, v2, v3 offset0:136 offset1:204
	v_pk_mul_f32 v[4:5], v[4:5], v[234:235]
	v_pk_mul_f32 v[6:7], v[6:7], v[236:237]
	v_pk_mul_f32 v[20:21], v[20:21], v[234:235]
	v_pk_mul_f32 v[22:23], v[22:23], v[236:237]
	v_mul_f32_e32 v242, 0xbfb8aa3b, v4
	v_mul_f32_e32 v243, 0xbfb8aa3b, v5
	v_mul_f32_e32 v244, 0xbfb8aa3b, v6
	v_mul_f32_e32 v245, 0xbfb8aa3b, v7
	v_exp_f32_e32 v242, v242
	v_exp_f32_e32 v243, v243
	v_exp_f32_e32 v244, v244
	v_exp_f32_e32 v245, v245
	v_add_f32_e32 v242, 1.0, v242
	v_add_f32_e32 v243, 1.0, v243
	v_add_f32_e32 v244, 1.0, v244
	v_add_f32_e32 v245, 1.0, v245
	v_rcp_f32_e32 v242, v242
	v_rcp_f32_e32 v243, v243
	v_rcp_f32_e32 v244, v244
	v_rcp_f32_e32 v245, v245
	s_nop 0
	v_pk_mul_f32 v[4:5], v[4:5], v[242:243]
	v_pk_mul_f32 v[6:7], v[6:7], v[244:245]
	v_pk_mul_f32 v[4:5], v[20:21], v[4:5]
	v_pk_mul_f32 v[6:7], v[22:23], v[6:7]
	ds_write2_b32 v198, v4, v5 offset0:16 offset1:84
	ds_write2_b32 v198, v6, v7 offset0:152 offset1:220
	v_pk_mul_f32 v[8:9], v[8:9], v[234:235]
	v_pk_mul_f32 v[10:11], v[10:11], v[236:237]
	v_pk_mul_f32 v[24:25], v[24:25], v[234:235]
	v_pk_mul_f32 v[26:27], v[26:27], v[236:237]
	v_mul_f32_e32 v242, 0xbfb8aa3b, v8
	v_mul_f32_e32 v243, 0xbfb8aa3b, v9
	v_mul_f32_e32 v244, 0xbfb8aa3b, v10
	v_mul_f32_e32 v245, 0xbfb8aa3b, v11
	v_exp_f32_e32 v242, v242
	v_exp_f32_e32 v243, v243
	v_exp_f32_e32 v244, v244
	v_exp_f32_e32 v245, v245
	v_add_f32_e32 v242, 1.0, v242
	v_add_f32_e32 v243, 1.0, v243
	v_add_f32_e32 v244, 1.0, v244
	v_add_f32_e32 v245, 1.0, v245
	v_rcp_f32_e32 v242, v242
	v_rcp_f32_e32 v243, v243
	v_rcp_f32_e32 v244, v244
	v_rcp_f32_e32 v245, v245
	s_nop 0
	v_pk_mul_f32 v[8:9], v[8:9], v[242:243]
	v_pk_mul_f32 v[10:11], v[10:11], v[244:245]
	v_pk_mul_f32 v[8:9], v[24:25], v[8:9]
	v_pk_mul_f32 v[10:11], v[26:27], v[10:11]
	ds_write2_b32 v198, v8, v9 offset0:32 offset1:100
	ds_write2_b32 v198, v10, v11 offset0:168 offset1:236
	v_pk_mul_f32 v[12:13], v[12:13], v[234:235]
	v_pk_mul_f32 v[14:15], v[14:15], v[236:237]
	v_pk_mul_f32 v[28:29], v[28:29], v[234:235]
	v_pk_mul_f32 v[30:31], v[30:31], v[236:237]
	v_mul_f32_e32 v242, 0xbfb8aa3b, v12
	v_mul_f32_e32 v243, 0xbfb8aa3b, v13
	v_mul_f32_e32 v244, 0xbfb8aa3b, v14
	v_mul_f32_e32 v245, 0xbfb8aa3b, v15
	v_exp_f32_e32 v242, v242
	v_exp_f32_e32 v243, v243
	v_exp_f32_e32 v244, v244
	v_exp_f32_e32 v245, v245
	v_add_f32_e32 v242, 1.0, v242
	v_add_f32_e32 v243, 1.0, v243
	v_add_f32_e32 v244, 1.0, v244
	v_add_f32_e32 v245, 1.0, v245
	v_rcp_f32_e32 v242, v242
	v_rcp_f32_e32 v243, v243
	v_rcp_f32_e32 v244, v244
	v_rcp_f32_e32 v245, v245
	s_nop 0
	v_pk_mul_f32 v[12:13], v[12:13], v[242:243]
	v_pk_mul_f32 v[14:15], v[14:15], v[244:245]
	v_pk_mul_f32 v[12:13], v[28:29], v[12:13]
	v_pk_mul_f32 v[14:15], v[30:31], v[14:15]
	ds_write2_b32 v198, v12, v13 offset0:48 offset1:116
	ds_write2_b32 v198, v14, v15 offset0:184 offset1:252
	v_pk_mul_f32 v[32:33], v[32:33], v[238:239]
	v_pk_mul_f32 v[34:35], v[34:35], v[240:241]
	v_pk_mul_f32 v[48:49], v[48:49], v[238:239]
	v_pk_mul_f32 v[50:51], v[50:51], v[240:241]
	v_mul_f32_e32 v242, 0xbfb8aa3b, v32
	v_mul_f32_e32 v243, 0xbfb8aa3b, v33
	v_mul_f32_e32 v244, 0xbfb8aa3b, v34
	v_mul_f32_e32 v245, 0xbfb8aa3b, v35
	v_exp_f32_e32 v242, v242
	v_exp_f32_e32 v243, v243
	v_exp_f32_e32 v244, v244
	v_exp_f32_e32 v245, v245
	v_add_f32_e32 v242, 1.0, v242
	v_add_f32_e32 v243, 1.0, v243
	v_add_f32_e32 v244, 1.0, v244
	v_add_f32_e32 v245, 1.0, v245
	v_rcp_f32_e32 v242, v242
	v_rcp_f32_e32 v243, v243
	v_rcp_f32_e32 v244, v244
	v_rcp_f32_e32 v245, v245
	s_nop 0
	v_pk_mul_f32 v[32:33], v[32:33], v[242:243]
	v_pk_mul_f32 v[34:35], v[34:35], v[244:245]
	v_pk_mul_f32 v[32:33], v[48:49], v[32:33]
	v_pk_mul_f32 v[34:35], v[50:51], v[34:35]
	ds_write2_b32 v199, v32, v33 offset0:0 offset1:68
	ds_write2_b32 v199, v34, v35 offset0:136 offset1:204
	v_pk_mul_f32 v[36:37], v[36:37], v[238:239]
	v_pk_mul_f32 v[38:39], v[38:39], v[240:241]
	v_pk_mul_f32 v[52:53], v[52:53], v[238:239]
	v_pk_mul_f32 v[54:55], v[54:55], v[240:241]
	v_mul_f32_e32 v242, 0xbfb8aa3b, v36
	v_mul_f32_e32 v243, 0xbfb8aa3b, v37
; DI void epi_slab(const GemmCfg c, const f32x16 (&acc)[4], float* sW, const float* rss, const size_t row0, const int g, const int lane,
;                  float* const g_h, u16* const g_hb, float* const g_out, const int final_out) {
;     ...
;   if (c.epi == EPI_SWIGLU) {
;     const int c4 = (ln_ & 15) * 4;
; #pragma unroll 2
;     for (int it = 0; it < 8; ++it) {
;       const int r = (ln_ >> 4) + 4 * it;
;       const float rs = rsqrtf(rss[r] * invK + 1e-6f);
;       f32x4 a = *(const f32x4*)(sW + r * 132 + c4);
;       f32x4 b = *(const f32x4*)(sW + r * 132 + 64 + c4);
;       float y[4];
; #pragma unroll
;       for (int e = 0; e < 4; ++e) { float av = a[e] * rs, bv = b[e] * rs; y[e] = av * __builtin_amdgcn_rcpf(1.f + __expf(-av)) * bv; }
;       *(u32x2*)(c.o16 + (row0 + r) * DFF + g * 64 + c4) = MK2(pack2(y[0], y[1]), pack2(y[2], y[3]));
;     }
; DI void gemm_run(const GemmCfg c, char* smem, float* const g_h, u16* const g_hb, float* const g_out, const int final_out) {
;     ...
;     f32x16 acc[2][4];
; #pragma unroll
;     for (int a = 0; a < 2; ++a)
; #pragma unroll
;       for (int b = 0; b < 4; ++b)
; #pragma unroll
;         for (int i = 0; i < 16; ++i) acc[a][b][i] = 0.f;
	v_mul_f32_e32 v244, 0xbfb8aa3b, v38
	v_mul_f32_e32 v245, 0xbfb8aa3b, v39
	v_exp_f32_e32 v242, v242
	v_exp_f32_e32 v243, v243
	v_exp_f32_e32 v244, v244
	v_exp_f32_e32 v245, v245
	v_add_f32_e32 v242, 1.0, v242
	v_add_f32_e32 v243, 1.0, v243
	v_add_f32_e32 v244, 1.0, v244
	v_add_f32_e32 v245, 1.0, v245
	v_rcp_f32_e32 v242, v242
	v_rcp_f32_e32 v243, v243
	v_rcp_f32_e32 v244, v244
	v_rcp_f32_e32 v245, v245
	s_nop 0
	v_pk_mul_f32 v[36:37], v[36:37], v[242:243]
	v_pk_mul_f32 v[38:39], v[38:39], v[244:245]
	v_pk_mul_f32 v[36:37], v[52:53], v[36:37]
	v_pk_mul_f32 v[38:39], v[54:55], v[38:39]
	ds_write2_b32 v199, v36, v37 offset0:16 offset1:84
	ds_write2_b32 v199, v38, v39 offset0:152 offset1:220
	v_pk_mul_f32 v[40:41], v[40:41], v[238:239]
	v_pk_mul_f32 v[42:43], v[42:43], v[240:241]
	v_pk_mul_f32 v[56:57], v[56:57], v[238:239]
	v_pk_mul_f32 v[58:59], v[58:59], v[240:241]
	v_mul_f32_e32 v242, 0xbfb8aa3b, v40
	v_mul_f32_e32 v243, 0xbfb8aa3b, v41
	v_mul_f32_e32 v244, 0xbfb8aa3b, v42
	v_mul_f32_e32 v245, 0xbfb8aa3b, v43
	v_exp_f32_e32 v242, v242
	v_exp_f32_e32 v243, v243
	v_exp_f32_e32 v244, v244
	v_exp_f32_e32 v245, v245
	v_add_f32_e32 v242, 1.0, v242
	v_add_f32_e32 v243, 1.0, v243
	v_add_f32_e32 v244, 1.0, v244
	v_add_f32_e32 v245, 1.0, v245
	v_rcp_f32_e32 v242, v242
	v_rcp_f32_e32 v243, v243
	v_rcp_f32_e32 v244, v244
	v_rcp_f32_e32 v245, v245
	s_nop 0
	v_pk_mul_f32 v[40:41], v[40:41], v[242:243]
	v_pk_mul_f32 v[42:43], v[42:43], v[244:245]
	v_pk_mul_f32 v[40:41], v[56:57], v[40:41]
	v_pk_mul_f32 v[42:43], v[58:59], v[42:43]
	ds_write2_b32 v199, v40, v41 offset0:32 offset1:100
	ds_write2_b32 v199, v42, v43 offset0:168 offset1:236
	v_pk_mul_f32 v[44:45], v[44:45], v[238:239]
	v_pk_mul_f32 v[46:47], v[46:47], v[240:241]
	v_pk_mul_f32 v[60:61], v[60:61], v[238:239]
	v_pk_mul_f32 v[62:63], v[62:63], v[240:241]
	v_mul_f32_e32 v242, 0xbfb8aa3b, v44
	v_mul_f32_e32 v243, 0xbfb8aa3b, v45
	v_mul_f32_e32 v244, 0xbfb8aa3b, v46
	v_mul_f32_e32 v245, 0xbfb8aa3b, v47
	v_exp_f32_e32 v242, v242
	v_exp_f32_e32 v243, v243
	v_exp_f32_e32 v244, v244
	v_exp_f32_e32 v245, v245
	v_add_f32_e32 v242, 1.0, v242
	v_add_f32_e32 v243, 1.0, v243
	v_add_f32_e32 v244, 1.0, v244
	v_add_f32_e32 v245, 1.0, v245
	v_rcp_f32_e32 v242, v242
	v_rcp_f32_e32 v243, v243
	v_rcp_f32_e32 v244, v244
	v_rcp_f32_e32 v245, v245
	s_nop 0
	v_pk_mul_f32 v[44:45], v[44:45], v[242:243]
	v_pk_mul_f32 v[46:47], v[46:47], v[244:245]
	v_pk_mul_f32 v[44:45], v[60:61], v[44:45]
	v_pk_mul_f32 v[46:47], v[62:63], v[46:47]
	ds_write2_b32 v199, v44, v45 offset0:48 offset1:116
	ds_write2_b32 v199, v46, v47 offset0:184 offset1:252
	v_mov_b32_e32 v0, 0
	v_mov_b32_e32 v1, 0
	v_mov_b32_e32 v2, 0
	v_mov_b32_e32 v3, 0
	v_mov_b32_e32 v4, 0
	v_mov_b32_e32 v5, 0
	v_mov_b32_e32 v6, 0
	v_mov_b32_e32 v7, 0
	v_mov_b32_e32 v8, 0
	v_mov_b32_e32 v9, 0
	v_mov_b32_e32 v10, 0
	v_mov_b32_e32 v11, 0
	v_mov_b32_e32 v12, 0
	v_mov_b32_e32 v13, 0
	v_mov_b32_e32 v14, 0
	v_mov_b32_e32 v15, 0
	v_mov_b32_e32 v32, 0
	v_mov_b32_e32 v33, 0
	v_mov_b32_e32 v34, 0
	v_mov_b32_e32 v35, 0
	v_mov_b32_e32 v36, 0
	v_mov_b32_e32 v37, 0
	v_mov_b32_e32 v38, 0
	v_mov_b32_e32 v39, 0
	v_mov_b32_e32 v40, 0
	v_mov_b32_e32 v41, 0
	v_mov_b32_e32 v42, 0
	v_mov_b32_e32 v43, 0
	v_mov_b32_e32 v44, 0
	v_mov_b32_e32 v45, 0
	v_mov_b32_e32 v46, 0
	v_mov_b32_e32 v47, 0
	v_mov_b32_e32 v80, 0
	v_mov_b32_e32 v81, 0
	v_mov_b32_e32 v82, 0
	v_mov_b32_e32 v83, 0
	v_mov_b32_e32 v84, 0
	v_mov_b32_e32 v85, 0
	v_mov_b32_e32 v86, 0
	v_mov_b32_e32 v87, 0
	v_mov_b32_e32 v88, 0
	v_mov_b32_e32 v89, 0
	v_mov_b32_e32 v90, 0
	v_mov_b32_e32 v91, 0
	v_mov_b32_e32 v92, 0
	v_mov_b32_e32 v93, 0
	v_mov_b32_e32 v94, 0
	v_mov_b32_e32 v95, 0
	v_mov_b32_e32 v112, 0
	v_mov_b32_e32 v113, 0
	v_mov_b32_e32 v114, 0
	v_mov_b32_e32 v115, 0
	v_mov_b32_e32 v116, 0
	v_mov_b32_e32 v117, 0
	v_mov_b32_e32 v118, 0
	v_mov_b32_e32 v119, 0
	v_mov_b32_e32 v120, 0
	v_mov_b32_e32 v121, 0
	v_mov_b32_e32 v122, 0
	v_mov_b32_e32 v123, 0
	v_mov_b32_e32 v124, 0
	v_mov_b32_e32 v125, 0
	v_mov_b32_e32 v126, 0
	v_mov_b32_e32 v127, 0
	s_waitcnt lgkmcnt(0)
; DI void epi_slab(const GemmCfg c, const f32x16 (&acc)[4], float* sW, const float* rss, const size_t row0, const int g, const int lane,
;                  float* const g_h, u16* const g_hb, float* const g_out, const int final_out) {
;     ...
;   if (c.epi == EPI_SWIGLU) {
;     const int c4 = (ln_ & 15) * 4;
; #pragma unroll 2
;     for (int it = 0; it < 8; ++it) {
;       const int r = (ln_ >> 4) + 4 * it;
;       const float rs = rsqrtf(rss[r] * invK + 1e-6f);
;       f32x4 a = *(const f32x4*)(sW + r * 132 + c4);
;       f32x4 b = *(const f32x4*)(sW + r * 132 + 64 + c4);
;       float y[4];
; #pragma unroll
;       for (int e = 0; e < 4; ++e) { float av = a[e] * rs, bv = b[e] * rs; y[e] = av * __builtin_amdgcn_rcpf(1.f + __expf(-av)) * bv; }
;       *(u32x2*)(c.o16 + (row0 + r) * DFF + g * 64 + c4) = MK2(pack2(y[0], y[1]), pack2(y[2], y[3]));
;     }
; DI void gemm_run(const GemmCfg c, char* smem, float* const g_h, u16* const g_hb, float* const g_out, const int final_out) {
;     ...
;     f32x16 acc[2][4];
; #pragma unroll
;     for (int a = 0; a < 2; ++a)
; #pragma unroll
;       for (int b = 0; b < 4; ++b)
; #pragma unroll
;         for (int i = 0; i < 16; ++i) acc[a][b][i] = 0.f;
	ds_read_b128 v[16:19], v200
	ds_read_b128 v[20:23], v200 offset:1088
	ds_read_b128 v[24:27], v200 offset:2176
	ds_read_b128 v[28:31], v200 offset:3264
	ds_read_b128 v[48:51], v200 offset:4352
	ds_read_b128 v[52:55], v200 offset:5440
	ds_read_b128 v[56:59], v200 offset:6528
	ds_read_b128 v[60:63], v200 offset:7616
	s_waitcnt lgkmcnt(7)
	v_lshl_add_u64 v[204:205], v[202:203], 0, s[8:9]
	v_cvt_pk_bf16_f32 v16, v16, v17
	v_cvt_pk_bf16_f32 v17, v18, v19
	s_add_u32 s8, s8, 0x5800
	s_addc_u32 s9, s9, 0
	global_store_dwordx2 v[204:205], v[16:17], off
	s_waitcnt lgkmcnt(6)
	v_lshl_add_u64 v[204:205], v[202:203], 0, s[8:9]
	v_cvt_pk_bf16_f32 v20, v20, v21
	v_cvt_pk_bf16_f32 v21, v22, v23
	s_add_u32 s8, s8, 0x5800
	s_addc_u32 s9, s9, 0
	global_store_dwordx2 v[204:205], v[20:21], off
	s_waitcnt lgkmcnt(5)
	v_lshl_add_u64 v[204:205], v[202:203], 0, s[8:9]
	v_cvt_pk_bf16_f32 v24, v24, v25
	v_cvt_pk_bf16_f32 v25, v26, v27
	s_add_u32 s8, s8, 0x5800
	s_addc_u32 s9, s9, 0
	global_store_dwordx2 v[204:205], v[24:25], off
	s_waitcnt lgkmcnt(4)
	v_lshl_add_u64 v[204:205], v[202:203], 0, s[8:9]
	v_cvt_pk_bf16_f32 v28, v28, v29
	v_cvt_pk_bf16_f32 v29, v30, v31
	s_add_u32 s8, s8, 0x5800
	s_addc_u32 s9, s9, 0
	global_store_dwordx2 v[204:205], v[28:29], off
	s_waitcnt lgkmcnt(3)
	v_lshl_add_u64 v[204:205], v[202:203], 0, s[8:9]
	v_cvt_pk_bf16_f32 v48, v48, v49
	v_cvt_pk_bf16_f32 v49, v50, v51
	s_add_u32 s8, s8, 0x5800
	s_addc_u32 s9, s9, 0
	global_store_dwordx2 v[204:205], v[48:49], off
	s_waitcnt lgkmcnt(2)
	v_lshl_add_u64 v[204:205], v[202:203], 0, s[8:9]
	v_cvt_pk_bf16_f32 v52, v52, v53
	v_cvt_pk_bf16_f32 v53, v54, v55
	s_add_u32 s8, s8, 0x5800
	s_addc_u32 s9, s9, 0
	global_store_dwordx2 v[204:205], v[52:53], off
	s_waitcnt lgkmcnt(1)
	v_lshl_add_u64 v[204:205], v[202:203], 0, s[8:9]
	v_cvt_pk_bf16_f32 v56, v56, v57
	v_cvt_pk_bf16_f32 v57, v58, v59
	s_add_u32 s8, s8, 0x5800
	s_addc_u32 s9, s9, 0
	global_store_dwordx2 v[204:205], v[56:57], off
	s_waitcnt lgkmcnt(0)
	v_lshl_add_u64 v[204:205], v[202:203], 0, s[8:9]
	v_cvt_pk_bf16_f32 v60, v60, v61
	v_cvt_pk_bf16_f32 v61, v62, v63
	s_add_u32 s8, s8, 0x5800
	s_addc_u32 s9, s9, 0
	global_store_dwordx2 v[204:205], v[60:61], off
	v_mov_b32_e32 v140, 0
	v_mov_b32_e32 v141, 0
	v_mov_b32_e32 v142, 0
	v_mov_b32_e32 v143, 0
	v_mov_b32_e32 v144, 0
	v_mov_b32_e32 v145, 0
	v_mov_b32_e32 v146, 0
	v_mov_b32_e32 v147, 0
	v_mov_b32_e32 v148, 0
	v_mov_b32_e32 v149, 0
	v_mov_b32_e32 v150, 0
	v_mov_b32_e32 v151, 0
	v_mov_b32_e32 v152, 0
	v_mov_b32_e32 v153, 0
	v_mov_b32_e32 v154, 0
	v_mov_b32_e32 v155, 0
	v_mov_b32_e32 v16, 0
	v_mov_b32_e32 v17, 0
	v_mov_b32_e32 v18, 0
	v_mov_b32_e32 v19, 0
	v_mov_b32_e32 v20, 0
	v_mov_b32_e32 v21, 0
	v_mov_b32_e32 v22, 0
	v_mov_b32_e32 v23, 0
	v_mov_b32_e32 v24, 0
	v_mov_b32_e32 v25, 0
	v_mov_b32_e32 v26, 0
	v_mov_b32_e32 v27, 0
	v_mov_b32_e32 v28, 0
	v_mov_b32_e32 v29, 0
	v_mov_b32_e32 v30, 0
	v_mov_b32_e32 v31, 0
	v_mov_b32_e32 v48, 0
	v_mov_b32_e32 v49, 0
	v_mov_b32_e32 v50, 0
	v_mov_b32_e32 v51, 0
	v_mov_b32_e32 v52, 0
	v_mov_b32_e32 v53, 0
	v_mov_b32_e32 v54, 0
	v_mov_b32_e32 v55, 0
	v_mov_b32_e32 v56, 0
	v_mov_b32_e32 v57, 0
	v_mov_b32_e32 v58, 0
	v_mov_b32_e32 v59, 0
	v_mov_b32_e32 v60, 0
	v_mov_b32_e32 v61, 0
	v_mov_b32_e32 v62, 0
	v_mov_b32_e32 v63, 0
	s_branch .LBB0_108
